# v12: v10 + compiler's zeroing-guard vmcnt waits removed from all GEMM unit headers (no pending load targets an accumulator there; they drained the epilogue stores and the hoisted FF1 bias loads)
# speedup vs baseline: 1.0075x; 1.0039x over previous
.LBB0_268:
	s_ashr_i32 s39, s38, 31
	s_lshl_b64 s[0:1], s[38:39], 20
	s_add_u32 s40, s29, s0
	s_addc_u32 s41, s52, s1
	s_and_b64 s[0:1], s[4:5], exec
	s_cselect_b32 s1, s41, s9
	s_cselect_b32 s7, s40, s8
	s_ashr_i32 s37, s36, 31
	s_lshl_b64 s[42:43], s[36:37], 20
	s_add_u32 s42, s53, s42
	s_addc_u32 s43, s56, s43
	s_and_b64 s[46:47], s[4:5], exec
	s_cselect_b32 s11, s43, s45
	s_cselect_b32 s33, s42, s44
	s_add_u32 s37, s44, 0x100
	s_addc_u32 s39, s45, 0
	s_mov_b32 s72, -2
	v_mov_b64_e32 v[32:33], 0
	v_mov_b64_e32 v[34:35], 0
	v_mov_b64_e32 v[36:37], 0
	v_mov_b64_e32 v[38:39], 0
	v_mov_b64_e32 v[40:41], 0
	v_mov_b64_e32 v[42:43], 0
	v_mov_b64_e32 v[44:45], 0
	v_mov_b64_e32 v[46:47], 0
	v_mov_b64_e32 v[48:49], 0
	v_mov_b64_e32 v[50:51], 0
	v_mov_b64_e32 v[52:53], 0
	v_mov_b64_e32 v[54:55], 0
	v_mov_b64_e32 v[56:57], 0
	v_mov_b64_e32 v[58:59], 0
	v_mov_b64_e32 v[60:61], 0
	v_mov_b64_e32 v[62:63], 0
	v_mov_b64_e32 v[64:65], 0
	v_mov_b64_e32 v[66:67], 0
	v_mov_b64_e32 v[68:69], 0
	v_mov_b64_e32 v[70:71], 0
	v_mov_b64_e32 v[72:73], 0
	v_mov_b64_e32 v[74:75], 0
	v_mov_b64_e32 v[76:77], 0
	v_mov_b64_e32 v[78:79], 0
	v_mov_b64_e32 v[80:81], 0
	v_mov_b64_e32 v[82:83], 0
	v_mov_b64_e32 v[84:85], 0
	v_mov_b64_e32 v[86:87], 0
	v_mov_b64_e32 v[88:89], 0
	v_mov_b64_e32 v[90:91], 0
	v_mov_b64_e32 v[92:93], 0
	v_mov_b64_e32 v[94:95], 0
	v_mov_b64_e32 v[96:97], 0
	v_mov_b64_e32 v[98:99], 0
	v_mov_b64_e32 v[100:101], 0
	v_mov_b64_e32 v[102:103], 0
	v_mov_b64_e32 v[104:105], 0
	v_mov_b64_e32 v[106:107], 0
	v_mov_b64_e32 v[108:109], 0
	v_mov_b64_e32 v[110:111], 0
	v_mov_b64_e32 v[112:113], 0
	v_mov_b64_e32 v[114:115], 0
	v_mov_b64_e32 v[116:117], 0
	v_mov_b64_e32 v[118:119], 0
	v_mov_b64_e32 v[120:121], 0
	v_mov_b64_e32 v[122:123], 0
	v_mov_b64_e32 v[124:125], 0
	v_mov_b64_e32 v[126:127], 0
	v_mov_b64_e32 v[128:129], 0
	v_mov_b64_e32 v[130:131], 0
	v_mov_b64_e32 v[132:133], 0
	v_mov_b64_e32 v[134:135], 0
	v_mov_b64_e32 v[136:137], 0
	v_mov_b64_e32 v[138:139], 0
	v_mov_b64_e32 v[140:141], 0
	v_mov_b64_e32 v[142:143], 0
	v_mov_b64_e32 v[144:145], 0
	v_mov_b64_e32 v[146:147], 0
	v_mov_b64_e32 v[148:149], 0
	v_mov_b64_e32 v[150:151], 0
	v_mov_b64_e32 v[152:153], 0
	v_mov_b64_e32 v[154:155], 0
	v_mov_b64_e32 v[156:157], 0
	v_mov_b64_e32 v[158:159], 0
	s_cmp_eq_u32 s99, 1
	s_cbranch_scc0 .Lue_269
	s_mov_b32 s99, 0
	s_barrier

.LBB0_338:
	s_ashr_i32 s27, s26, 31
	s_lshl_b64 s[28:29], s[26:27], 20
	s_add_u32 s28, s47, s28
	s_addc_u32 s29, s48, s29
	s_and_b64 s[30:31], s[2:3], exec
	s_cselect_b32 s27, s29, s39
	s_cselect_b32 s58, s28, s38
	s_ashr_i32 s25, s24, 31
	s_lshl_b64 s[30:31], s[24:25], 20
	s_add_u32 s30, s33, s30
	s_addc_u32 s31, s46, s31
	s_and_b64 s[40:41], s[2:3], exec
	s_cselect_b32 s25, s31, s37
	s_cselect_b32 s59, s30, s36
	s_add_u32 s60, s36, 0x100
	s_addc_u32 s61, s37, 0
	s_mov_b32 s62, -2
	v_mov_b64_e32 v[0:1], 0
	v_mov_b64_e32 v[2:3], 0
	v_mov_b64_e32 v[4:5], 0
	v_mov_b64_e32 v[6:7], 0
	v_mov_b64_e32 v[8:9], 0
	v_mov_b64_e32 v[10:11], 0
	v_mov_b64_e32 v[12:13], 0
	v_mov_b64_e32 v[14:15], 0
	v_mov_b64_e32 v[16:17], 0
	v_mov_b64_e32 v[18:19], 0
	v_mov_b64_e32 v[20:21], 0
	v_mov_b64_e32 v[22:23], 0
	v_mov_b64_e32 v[24:25], 0
	v_mov_b64_e32 v[26:27], 0
	v_mov_b64_e32 v[28:29], 0
	v_mov_b64_e32 v[30:31], 0
	v_mov_b64_e32 v[32:33], 0
	v_mov_b64_e32 v[34:35], 0
	v_mov_b64_e32 v[36:37], 0
	v_mov_b64_e32 v[38:39], 0
	v_mov_b64_e32 v[40:41], 0
	v_mov_b64_e32 v[42:43], 0
	v_mov_b64_e32 v[44:45], 0
	v_mov_b64_e32 v[46:47], 0
	v_mov_b64_e32 v[48:49], 0
	v_mov_b64_e32 v[50:51], 0
	v_mov_b64_e32 v[52:53], 0
	v_mov_b64_e32 v[54:55], 0
	v_mov_b64_e32 v[56:57], 0
	v_mov_b64_e32 v[58:59], 0
	v_mov_b64_e32 v[60:61], 0
	v_mov_b64_e32 v[62:63], 0
	v_mov_b64_e32 v[64:65], 0
	v_mov_b64_e32 v[66:67], 0
	v_mov_b64_e32 v[68:69], 0
	v_mov_b64_e32 v[70:71], 0
	v_mov_b64_e32 v[72:73], 0
	v_mov_b64_e32 v[74:75], 0
	v_mov_b64_e32 v[76:77], 0
	v_mov_b64_e32 v[78:79], 0
	v_mov_b64_e32 v[80:81], 0
	v_mov_b64_e32 v[82:83], 0
	v_mov_b64_e32 v[84:85], 0
	v_mov_b64_e32 v[86:87], 0
	v_mov_b64_e32 v[88:89], 0
	v_mov_b64_e32 v[90:91], 0
	v_mov_b64_e32 v[92:93], 0
	v_mov_b64_e32 v[94:95], 0
	v_mov_b64_e32 v[96:97], 0
	v_mov_b64_e32 v[98:99], 0
	v_mov_b64_e32 v[100:101], 0
	v_mov_b64_e32 v[102:103], 0
	v_mov_b64_e32 v[104:105], 0
	v_mov_b64_e32 v[106:107], 0
	v_mov_b64_e32 v[108:109], 0
	v_mov_b64_e32 v[110:111], 0
	v_mov_b64_e32 v[112:113], 0
	v_mov_b64_e32 v[114:115], 0
	v_mov_b64_e32 v[116:117], 0
	v_mov_b64_e32 v[118:119], 0
	v_mov_b64_e32 v[120:121], 0
	v_mov_b64_e32 v[122:123], 0
	v_mov_b64_e32 v[124:125], 0
	v_mov_b64_e32 v[126:127], 0
	s_cmp_eq_u32 s99, 1
	s_cbranch_scc0 .Lue_339
	s_mov_b32 s99, 0
	s_barrier

.LBB0_1492:
	s_ashr_i32 s29, s28, 31
	s_lshl_b64 s[30:31], s[28:29], 20
	s_add_u32 s30, s25, s30
	s_addc_u32 s31, s33, s31
	s_and_b64 s[34:35], s[4:5], exec
	s_cselect_b32 s29, s31, s41
	s_cselect_b32 s37, s30, s40
	s_ashr_i32 s27, s26, 31
	s_lshl_b64 s[34:35], s[26:27], 20
	s_add_u32 s34, s48, s34
	s_addc_u32 s35, s49, s35
	s_and_b64 s[42:43], s[4:5], exec
	s_cselect_b32 s27, s35, s39
	s_cselect_b32 s57, s34, s38
	s_add_u32 s58, s38, 0x100
	s_addc_u32 s59, s39, 0
	s_mov_b32 s60, -2
	s_waitcnt lgkmcnt(0)
	v_mov_b64_e32 v[0:1], 0
	v_mov_b64_e32 v[2:3], 0
	v_mov_b64_e32 v[4:5], 0
	v_mov_b64_e32 v[6:7], 0
	v_mov_b64_e32 v[8:9], 0
	v_mov_b64_e32 v[10:11], 0
	v_mov_b64_e32 v[12:13], 0
	v_mov_b64_e32 v[14:15], 0
	v_mov_b64_e32 v[16:17], 0
	v_mov_b64_e32 v[18:19], 0
	v_mov_b64_e32 v[20:21], 0
	v_mov_b64_e32 v[22:23], 0
	v_mov_b64_e32 v[24:25], 0
	v_mov_b64_e32 v[26:27], 0
	v_mov_b64_e32 v[28:29], 0
	v_mov_b64_e32 v[30:31], 0
	v_mov_b64_e32 v[32:33], 0
	v_mov_b64_e32 v[34:35], 0
	v_mov_b64_e32 v[36:37], 0
	v_mov_b64_e32 v[38:39], 0
	v_mov_b64_e32 v[40:41], 0
	v_mov_b64_e32 v[42:43], 0
	v_mov_b64_e32 v[44:45], 0
	v_mov_b64_e32 v[46:47], 0
	v_mov_b64_e32 v[48:49], 0
	v_mov_b64_e32 v[50:51], 0
	v_mov_b64_e32 v[52:53], 0
	v_mov_b64_e32 v[54:55], 0
	v_mov_b64_e32 v[56:57], 0
	v_mov_b64_e32 v[58:59], 0
	v_mov_b64_e32 v[60:61], 0
	v_mov_b64_e32 v[62:63], 0
	v_mov_b64_e32 v[64:65], 0
	v_mov_b64_e32 v[66:67], 0
	v_mov_b64_e32 v[68:69], 0
	v_mov_b64_e32 v[70:71], 0
	v_mov_b64_e32 v[72:73], 0
	v_mov_b64_e32 v[74:75], 0
	v_mov_b64_e32 v[76:77], 0
	v_mov_b64_e32 v[78:79], 0
	v_mov_b64_e32 v[80:81], 0
	v_mov_b64_e32 v[82:83], 0
	v_mov_b64_e32 v[84:85], 0
	v_mov_b64_e32 v[86:87], 0
	v_mov_b64_e32 v[88:89], 0
	v_mov_b64_e32 v[90:91], 0
	v_mov_b64_e32 v[92:93], 0
	v_mov_b64_e32 v[94:95], 0
	v_mov_b64_e32 v[96:97], 0
	v_mov_b64_e32 v[98:99], 0
	v_mov_b64_e32 v[100:101], 0
	v_mov_b64_e32 v[102:103], 0
	v_mov_b64_e32 v[104:105], 0
	v_mov_b64_e32 v[106:107], 0
	v_mov_b64_e32 v[108:109], 0
	v_mov_b64_e32 v[110:111], 0
	v_mov_b64_e32 v[112:113], 0
	v_mov_b64_e32 v[114:115], 0
	v_mov_b64_e32 v[116:117], 0
	v_mov_b64_e32 v[118:119], 0
	v_mov_b64_e32 v[120:121], 0
	v_mov_b64_e32 v[122:123], 0
	v_mov_b64_e32 v[124:125], 0
	v_mov_b64_e32 v[126:127], 0
	s_cmp_eq_u32 s99, 1
	s_cbranch_scc0 .Lue_1493
	s_mov_b32 s99, 0
	s_barrier

.LBB0_1604:
	s_ashr_i32 s25, s24, 31
	s_lshl_b64 s[26:27], s[24:25], 21
	s_add_u32 s26, s1, s26
	s_addc_u32 s27, s33, s27
	s_and_b64 s[28:29], s[4:5], exec
	s_cselect_b32 s25, s27, s35
	s_cselect_b32 s58, s26, s34
	s_ashr_i32 s23, s22, 31
	s_lshl_b64 s[28:29], s[22:23], 21
	s_add_u32 s28, s44, s28
	s_addc_u32 s29, s45, s29
	s_and_b64 s[38:39], s[4:5], exec
	s_cselect_b32 s23, s29, s37
	s_cselect_b32 s59, s28, s36
	s_add_u32 s60, s36, 0x100
	s_addc_u32 s61, s37, 0
	s_mov_b32 s62, -2
	v_mov_b64_e32 v[0:1], 0
	v_mov_b64_e32 v[2:3], 0
	v_mov_b64_e32 v[4:5], 0
	v_mov_b64_e32 v[6:7], 0
	v_mov_b64_e32 v[8:9], 0
	v_mov_b64_e32 v[10:11], 0
	v_mov_b64_e32 v[12:13], 0
	v_mov_b64_e32 v[14:15], 0
	v_mov_b64_e32 v[16:17], 0
	v_mov_b64_e32 v[18:19], 0
	v_mov_b64_e32 v[20:21], 0
	v_mov_b64_e32 v[22:23], 0
	v_mov_b64_e32 v[24:25], 0
	v_mov_b64_e32 v[26:27], 0
	v_mov_b64_e32 v[28:29], 0
	v_mov_b64_e32 v[30:31], 0
	v_mov_b64_e32 v[32:33], 0
	v_mov_b64_e32 v[34:35], 0
	v_mov_b64_e32 v[36:37], 0
	v_mov_b64_e32 v[38:39], 0
	v_mov_b64_e32 v[40:41], 0
	v_mov_b64_e32 v[42:43], 0
	v_mov_b64_e32 v[44:45], 0
	v_mov_b64_e32 v[46:47], 0
	v_mov_b64_e32 v[48:49], 0
	v_mov_b64_e32 v[50:51], 0
	v_mov_b64_e32 v[52:53], 0
	v_mov_b64_e32 v[54:55], 0
	v_mov_b64_e32 v[56:57], 0
	v_mov_b64_e32 v[58:59], 0
	v_mov_b64_e32 v[60:61], 0
	v_mov_b64_e32 v[62:63], 0
	v_mov_b64_e32 v[64:65], 0
	v_mov_b64_e32 v[66:67], 0
	v_mov_b64_e32 v[68:69], 0
	v_mov_b64_e32 v[70:71], 0
	v_mov_b64_e32 v[72:73], 0
	v_mov_b64_e32 v[74:75], 0
	v_mov_b64_e32 v[76:77], 0
	v_mov_b64_e32 v[78:79], 0
	v_mov_b64_e32 v[80:81], 0
	v_mov_b64_e32 v[82:83], 0
	v_mov_b64_e32 v[84:85], 0
	v_mov_b64_e32 v[86:87], 0
	v_mov_b64_e32 v[88:89], 0
	v_mov_b64_e32 v[90:91], 0
	v_mov_b64_e32 v[92:93], 0
	v_mov_b64_e32 v[94:95], 0
	v_mov_b64_e32 v[96:97], 0
	v_mov_b64_e32 v[98:99], 0
	v_mov_b64_e32 v[100:101], 0
	v_mov_b64_e32 v[102:103], 0
	v_mov_b64_e32 v[104:105], 0
	v_mov_b64_e32 v[106:107], 0
	v_mov_b64_e32 v[108:109], 0
	v_mov_b64_e32 v[110:111], 0
	v_mov_b64_e32 v[112:113], 0
	v_mov_b64_e32 v[114:115], 0
	v_mov_b64_e32 v[116:117], 0
	v_mov_b64_e32 v[118:119], 0
	v_mov_b64_e32 v[128:129], 0
	v_mov_b64_e32 v[130:131], 0
	v_mov_b64_e32 v[132:133], 0
	v_mov_b64_e32 v[134:135], 0
	s_cmp_eq_u32 s99, 1
	s_cbranch_scc0 .Lue_1605
	s_mov_b32 s99, 0
	s_barrier

.LBB0_1680:
	s_ashr_i32 s15, s14, 31
	s_lshl_b64 s[16:17], s[14:15], 23
	s_add_u32 s16, s36, s16
	s_addc_u32 s17, s37, s17
	s_and_b64 s[18:19], s[0:1], exec
	s_cselect_b32 s15, s17, s23
	s_cselect_b32 s41, s16, s22
	s_ashr_i32 s13, s12, 31
	s_lshl_b64 s[18:19], s[12:13], 23
	s_add_u32 s18, s34, s18
	s_addc_u32 s19, s35, s19
	s_and_b64 s[26:27], s[0:1], exec
	s_cselect_b32 s13, s19, s25
	s_cselect_b32 s42, s18, s24
	s_add_u32 s43, s24, 0x100
	s_addc_u32 s44, s25, 0
	s_mov_b32 s45, -2
	v_mov_b64_e32 v[0:1], 0
	v_mov_b64_e32 v[2:3], 0
	v_mov_b64_e32 v[4:5], 0
	v_mov_b64_e32 v[6:7], 0
	v_mov_b64_e32 v[8:9], 0
	v_mov_b64_e32 v[10:11], 0
	v_mov_b64_e32 v[12:13], 0
	v_mov_b64_e32 v[14:15], 0
	v_mov_b64_e32 v[16:17], 0
	v_mov_b64_e32 v[18:19], 0
	v_mov_b64_e32 v[20:21], 0
	v_mov_b64_e32 v[22:23], 0
	v_mov_b64_e32 v[24:25], 0
	v_mov_b64_e32 v[26:27], 0
	v_mov_b64_e32 v[28:29], 0
	v_mov_b64_e32 v[30:31], 0
	v_mov_b64_e32 v[32:33], 0
	v_mov_b64_e32 v[34:35], 0
	v_mov_b64_e32 v[36:37], 0
	v_mov_b64_e32 v[38:39], 0
	v_mov_b64_e32 v[40:41], 0
	v_mov_b64_e32 v[42:43], 0
	v_mov_b64_e32 v[44:45], 0
	v_mov_b64_e32 v[46:47], 0
	v_mov_b64_e32 v[48:49], 0
	v_mov_b64_e32 v[50:51], 0
	v_mov_b64_e32 v[52:53], 0
	v_mov_b64_e32 v[54:55], 0
	v_mov_b64_e32 v[56:57], 0
	v_mov_b64_e32 v[58:59], 0
	v_mov_b64_e32 v[60:61], 0
	v_mov_b64_e32 v[62:63], 0
	v_mov_b64_e32 v[64:65], 0
	v_mov_b64_e32 v[66:67], 0
	v_mov_b64_e32 v[68:69], 0
	v_mov_b64_e32 v[70:71], 0
	v_mov_b64_e32 v[72:73], 0
	v_mov_b64_e32 v[74:75], 0
	v_mov_b64_e32 v[76:77], 0
	v_mov_b64_e32 v[78:79], 0
	v_mov_b64_e32 v[80:81], 0
	v_mov_b64_e32 v[82:83], 0
	v_mov_b64_e32 v[84:85], 0
	v_mov_b64_e32 v[86:87], 0
	v_mov_b64_e32 v[88:89], 0
	v_mov_b64_e32 v[90:91], 0
	v_mov_b64_e32 v[92:93], 0
	v_mov_b64_e32 v[94:95], 0
	v_mov_b64_e32 v[96:97], 0
	v_mov_b64_e32 v[98:99], 0
	v_mov_b64_e32 v[100:101], 0
	v_mov_b64_e32 v[102:103], 0
	v_mov_b64_e32 v[104:105], 0
	v_mov_b64_e32 v[106:107], 0
	v_mov_b64_e32 v[108:109], 0
	v_mov_b64_e32 v[110:111], 0
	v_mov_b64_e32 v[112:113], 0
	v_mov_b64_e32 v[114:115], 0
	v_mov_b64_e32 v[116:117], 0
	v_mov_b64_e32 v[118:119], 0
	v_mov_b64_e32 v[120:121], 0
	v_mov_b64_e32 v[122:123], 0
	v_mov_b64_e32 v[124:125], 0
	v_mov_b64_e32 v[126:127], 0
	s_cmp_eq_u32 s99, 1
	s_cbranch_scc0 .Lue_1681
	s_mov_b32 s99, 0
	s_barrier
